# GEMM main loop: per-segment s_setprio 1/0 toggling around the MFMA blocks removed (31 instructions), bit-identical
# speedup vs baseline: 1.0035x; 1.0035x over previous
; #define G_STAGE(P, RS, br, kt) do { const int _so = ((br) * G_K + (kt) * G_BK) * 2; \
;     __builtin_amdgcn_raw_ptr_buffer_load_lds(RS, (__attribute__((address_space(3))) unsigned*)((char*)(P) + tid * 16), 16, (int)voff0, _so, 0, 0); \
;     __builtin_amdgcn_raw_ptr_buffer_load_lds(RS, (__attribute__((address_space(3))) unsigned*)((char*)(P) + tid * 16 + 8192), 16, (int)voff1, _so, 0, 0); } while (0)
; #define G_LDA(dst, b, h) for (int m = 0; m < 4; ++m) for (int k = 0; k < 2; ++k) \
;     dst[m][k] = *reinterpret_cast<const bf16x8*>((char*)G_SA(b, h) + lds_byte(wr * 64 + m * 16 + fr, k * 32 + fq * 8))
; #define G_LDB(dst, b, h) for (int n = 0; n < 2; ++n) for (int k = 0; k < 2; ++k) \
;     dst[n][k] = *reinterpret_cast<const bf16x8*>((char*)G_SB(b, h) + lds_byte(wc * 32 + n * 16 + fr, k * 32 + fq * 8))
; #define G_MMA(ai, bj, At, Bt_) do { __builtin_amdgcn_s_setprio(1); \
;     for (int m = 0; m < 4; ++m) for (int n = 0; n < 2; ++n) for (int k = 0; k < 2; ++k) \
;       acc[ai][bj][m][n] = __builtin_amdgcn_mfma_f32_16x16x32_bf16(Bt_[n][k], At[m][k], acc[ai][bj][m][n], 0, 0, 0); \
;     __builtin_amdgcn_s_setprio(0); } while (0)
; #define WAIT_V(n) asm volatile("s_waitcnt vmcnt(" #n ")" ::: "memory")
; #define WAIT_L(n) asm volatile("s_waitcnt lgkmcnt(" #n ")" ::: "memory")
; #define G_BAR __builtin_amdgcn_s_barrier()
; #define G_SCHED __builtin_amdgcn_sched_barrier(0)
; DEV void phase_gemm(const Params& p, int l, int mode) {
;     ...
;       G_LDB(B0, 0, 0); G_SCHED; G_LDA(At, 0, 0); G_STAGE(G_SA(1, 1), A, brow + G_HALF, t + 1);
;       WAIT_L(8); G_BAR; WAIT_L(0); G_MMA(0, 0, At, B0); G_BAR; G_SCHED;
;       G_LDB(B1, 0, 1); G_STAGE(G_SB(0, 0), Bt, bcol, t + 2);
;       G_BAR; WAIT_L(0); G_MMA(0, 1, At, B1); G_BAR;
;       G_LDA(At, 0, 1); G_STAGE(G_SA(0, 0), A, brow, t + 2);
;       G_BAR; WAIT_L(0); G_MMA(1, 0, At, B0); G_BAR; G_SCHED;
;       G_STAGE(G_SB(0, 1), Bt, bcol + G_HALF, t + 2);
;       WAIT_V(6); G_BAR; G_MMA(1, 1, At, B1); G_BAR;
.LBB0_211:
	ds_read_b128 v[128:131], v216
	ds_read_b128 v[132:135], v216 offset:1024
	ds_read_b128 v[136:139], v216 offset:2048
	ds_read_b128 v[140:143], v216 offset:3072
	s_add_i32 s12, s8, s11
	v_readfirstlane_b32 s19, v214
	s_add_i32 s13, s12, 0x40080
	s_mov_b32 m0, s19
	v_readfirstlane_b32 s19, v215
	ds_read_b128 v[144:147], v217
	ds_read_b128 v[148:151], v217 offset:1024
	ds_read_b128 v[152:155], v218
	ds_read_b128 v[156:159], v218 offset:1024
	ds_read_b128 v[168:171], v219
	ds_read_b128 v[172:175], v219 offset:1024
	ds_read_b128 v[176:179], v220
	ds_read_b128 v[180:183], v220 offset:1024
	buffer_load_dwordx4 v198, s[68:71], s13 offen lds
	s_mov_b32 m0, s19
	s_nop 0
	buffer_load_dwordx4 v199, s[68:71], s13 offen lds
	s_waitcnt lgkmcnt(8)
	s_barrier
	s_waitcnt lgkmcnt(0)
	s_waitcnt lgkmcnt(7)
	v_mfma_f32_16x16x32_bf16 v[124:127], v[128:131], v[144:147], v[124:127]
	v_mfma_f32_16x16x32_bf16 v[120:123], v[136:139], v[144:147], v[120:123]
	s_waitcnt lgkmcnt(5)
	v_mfma_f32_16x16x32_bf16 v[116:119], v[128:131], v[152:155], v[116:119]
	v_mfma_f32_16x16x32_bf16 v[112:115], v[136:139], v[152:155], v[112:115]
	s_waitcnt lgkmcnt(3)
	v_mfma_f32_16x16x32_bf16 v[108:111], v[128:131], v[168:171], v[108:111]
	v_mfma_f32_16x16x32_bf16 v[104:107], v[136:139], v[168:171], v[104:107]
	s_waitcnt lgkmcnt(1)
	v_mfma_f32_16x16x32_bf16 v[100:103], v[128:131], v[176:179], v[100:103]
	v_mfma_f32_16x16x32_bf16 v[96:99], v[136:139], v[176:179], v[96:99]
	v_mfma_f32_16x16x32_bf16 v[124:127], v[132:135], v[148:151], v[124:127]
	v_mfma_f32_16x16x32_bf16 v[120:123], v[140:143], v[148:151], v[120:123]
	v_mfma_f32_16x16x32_bf16 v[116:119], v[132:135], v[156:159], v[116:119]
	v_mfma_f32_16x16x32_bf16 v[112:115], v[140:143], v[156:159], v[112:115]
	v_mfma_f32_16x16x32_bf16 v[108:111], v[132:135], v[172:175], v[108:111]
	v_mfma_f32_16x16x32_bf16 v[104:107], v[140:143], v[172:175], v[104:107]
	s_waitcnt lgkmcnt(0)
	v_mfma_f32_16x16x32_bf16 v[100:103], v[132:135], v[180:183], v[100:103]
	v_mfma_f32_16x16x32_bf16 v[96:99], v[140:143], v[180:183], v[96:99]
	s_barrier
	s_add_i32 s13, s9, s11
	v_readfirstlane_b32 s22, v200
	s_add_i32 s19, s13, 0x100
	s_mov_b32 s74, s70
	s_mov_b32 s75, s71
	s_mov_b32 m0, s22
	v_readfirstlane_b32 s22, v201
	ds_read_b128 v[224:227], v221
	ds_read_b128 v[228:231], v221 offset:1024
	ds_read_b128 v[232:235], v221 offset:2048
	ds_read_b128 v[236:239], v221 offset:3072
	buffer_load_dwordx4 v198, s[72:75], s19 offen lds
	s_mov_b32 m0, s22
	s_nop 0
	buffer_load_dwordx4 v199, s[72:75], s19 offen lds
	s_barrier
	s_waitcnt lgkmcnt(0)
	s_waitcnt lgkmcnt(3)
	v_mfma_f32_16x16x32_bf16 v[92:95], v[224:227], v[144:147], v[92:95]
	s_waitcnt lgkmcnt(1)
	v_mfma_f32_16x16x32_bf16 v[88:91], v[232:235], v[144:147], v[88:91]
	v_mfma_f32_16x16x32_bf16 v[84:87], v[224:227], v[152:155], v[84:87]
	v_mfma_f32_16x16x32_bf16 v[80:83], v[232:235], v[152:155], v[80:83]
	v_mfma_f32_16x16x32_bf16 v[76:79], v[224:227], v[168:171], v[76:79]
	v_mfma_f32_16x16x32_bf16 v[72:75], v[232:235], v[168:171], v[72:75]
	v_mfma_f32_16x16x32_bf16 v[68:71], v[224:227], v[176:179], v[68:71]
	v_mfma_f32_16x16x32_bf16 v[64:67], v[232:235], v[176:179], v[64:67]
	v_mfma_f32_16x16x32_bf16 v[92:95], v[228:231], v[148:151], v[92:95]
	s_waitcnt lgkmcnt(0)
	v_mfma_f32_16x16x32_bf16 v[88:91], v[236:239], v[148:151], v[88:91]
	v_mfma_f32_16x16x32_bf16 v[84:87], v[228:231], v[156:159], v[84:87]
	v_mfma_f32_16x16x32_bf16 v[80:83], v[236:239], v[156:159], v[80:83]
	v_mfma_f32_16x16x32_bf16 v[76:79], v[228:231], v[172:175], v[76:79]
	v_mfma_f32_16x16x32_bf16 v[72:75], v[236:239], v[172:175], v[72:75]
	v_mfma_f32_16x16x32_bf16 v[68:71], v[228:231], v[180:183], v[68:71]
	v_mfma_f32_16x16x32_bf16 v[64:67], v[236:239], v[180:183], v[64:67]
	v_readfirstlane_b32 s22, v202
	s_add_i32 s19, s12, 0x100
	s_mov_b32 m0, s22
	v_readfirstlane_b32 s22, v203
	s_barrier
	ds_read_b128 v[144:147], v217 offset:16384
	ds_read_b128 v[148:151], v217 offset:17408
	ds_read_b128 v[152:155], v218 offset:16384
	ds_read_b128 v[156:159], v218 offset:17408
	ds_read_b128 v[168:171], v219 offset:16384
	ds_read_b128 v[172:175], v219 offset:17408
	ds_read_b128 v[176:179], v220 offset:16384
	ds_read_b128 v[180:183], v220 offset:17408
	buffer_load_dwordx4 v198, s[68:71], s19 offen lds
	s_mov_b32 m0, s22
	s_nop 0
	buffer_load_dwordx4 v199, s[68:71], s19 offen lds
	s_barrier
	s_waitcnt lgkmcnt(0)
	s_waitcnt lgkmcnt(7)
	v_mfma_f32_16x16x32_bf16 v[60:63], v[128:131], v[144:147], v[60:63]
	v_mfma_f32_16x16x32_bf16 v[56:59], v[136:139], v[144:147], v[56:59]
	s_waitcnt lgkmcnt(5)
	v_mfma_f32_16x16x32_bf16 v[52:55], v[128:131], v[152:155], v[52:55]
	v_mfma_f32_16x16x32_bf16 v[48:51], v[136:139], v[152:155], v[48:51]
	s_waitcnt lgkmcnt(3)
	v_mfma_f32_16x16x32_bf16 v[44:47], v[128:131], v[168:171], v[44:47]
	v_mfma_f32_16x16x32_bf16 v[40:43], v[136:139], v[168:171], v[40:43]
	s_waitcnt lgkmcnt(1)
	v_mfma_f32_16x16x32_bf16 v[36:39], v[128:131], v[176:179], v[36:39]
	v_mfma_f32_16x16x32_bf16 v[32:35], v[136:139], v[176:179], v[32:35]
	v_mfma_f32_16x16x32_bf16 v[60:63], v[132:135], v[148:151], v[60:63]
	v_mfma_f32_16x16x32_bf16 v[56:59], v[140:143], v[148:151], v[56:59]
	v_mfma_f32_16x16x32_bf16 v[52:55], v[132:135], v[156:159], v[52:55]
	v_mfma_f32_16x16x32_bf16 v[48:51], v[140:143], v[156:159], v[48:51]
	v_mfma_f32_16x16x32_bf16 v[44:47], v[132:135], v[172:175], v[44:47]
	v_mfma_f32_16x16x32_bf16 v[40:43], v[140:143], v[172:175], v[40:43]
	s_waitcnt lgkmcnt(0)
	v_mfma_f32_16x16x32_bf16 v[36:39], v[132:135], v[180:183], v[36:39]
	v_mfma_f32_16x16x32_bf16 v[32:35], v[140:143], v[180:183], v[32:35]
	s_barrier
; #define G_STAGE(P, RS, br, kt) do { const int _so = ((br) * G_K + (kt) * G_BK) * 2; \
;     __builtin_amdgcn_raw_ptr_buffer_load_lds(RS, (__attribute__((address_space(3))) unsigned*)((char*)(P) + tid * 16), 16, (int)voff0, _so, 0, 0); \
;     __builtin_amdgcn_raw_ptr_buffer_load_lds(RS, (__attribute__((address_space(3))) unsigned*)((char*)(P) + tid * 16 + 8192), 16, (int)voff1, _so, 0, 0); } while (0)
; #define G_LDA(dst, b, h) for (int m = 0; m < 4; ++m) for (int k = 0; k < 2; ++k) \
;     dst[m][k] = *reinterpret_cast<const bf16x8*>((char*)G_SA(b, h) + lds_byte(wr * 64 + m * 16 + fr, k * 32 + fq * 8))
; #define G_LDB(dst, b, h) for (int n = 0; n < 2; ++n) for (int k = 0; k < 2; ++k) \
;     dst[n][k] = *reinterpret_cast<const bf16x8*>((char*)G_SB(b, h) + lds_byte(wc * 32 + n * 16 + fr, k * 32 + fq * 8))
; #define G_MMA(ai, bj, At, Bt_) do { __builtin_amdgcn_s_setprio(1); \
;     for (int m = 0; m < 4; ++m) for (int n = 0; n < 2; ++n) for (int k = 0; k < 2; ++k) \
;       acc[ai][bj][m][n] = __builtin_amdgcn_mfma_f32_16x16x32_bf16(Bt_[n][k], At[m][k], acc[ai][bj][m][n], 0, 0, 0); \
;     __builtin_amdgcn_s_setprio(0); } while (0)
; #define WAIT_V(n) asm volatile("s_waitcnt vmcnt(" #n ")" ::: "memory")
; #define WAIT_L(n) asm volatile("s_waitcnt lgkmcnt(" #n ")" ::: "memory")
; #define G_BAR __builtin_amdgcn_s_barrier()
; #define G_SCHED __builtin_amdgcn_sched_barrier(0)
; DEV void phase_gemm(const Params& p, int l, int mode) {
;     ...
;       WAIT_V(6); G_BAR; G_MMA(1, 1, At, B1); G_BAR;
;       G_LDB(B0, 1, 0); G_SCHED; G_LDA(At, 1, 0); G_STAGE(G_SA(0, 1), A, brow + G_HALF, t + 2);
;       WAIT_L(8); G_BAR; WAIT_L(0); G_MMA(0, 0, At, B0); G_BAR; G_SCHED;
;       G_LDB(B1, 1, 1); G_STAGE(G_SB(1, 0), Bt, bcol, t + 3);
;       G_BAR; WAIT_L(0); G_MMA(0, 1, At, B1); G_BAR;
;       G_LDA(At, 1, 1); G_STAGE(G_SA(1, 0), A, brow, t + 3);
;       G_BAR; WAIT_L(0); G_MMA(1, 0, At, B0); G_BAR; G_SCHED;
	v_readfirstlane_b32 s22, v204
	s_add_i32 s19, s13, 0x40100
	s_mov_b32 m0, s22
	v_readfirstlane_b32 s22, v205
	buffer_load_dwordx4 v198, s[72:75], s19 offen lds
	s_mov_b32 m0, s22
	s_nop 0
	buffer_load_dwordx4 v199, s[72:75], s19 offen lds
	s_waitcnt vmcnt(6)
	s_barrier
	v_mfma_f32_16x16x32_bf16 v[28:31], v[224:227], v[144:147], v[28:31]
	v_mfma_f32_16x16x32_bf16 v[24:27], v[232:235], v[144:147], v[24:27]
	v_mfma_f32_16x16x32_bf16 v[20:23], v[224:227], v[152:155], v[20:23]
	v_mfma_f32_16x16x32_bf16 v[16:19], v[232:235], v[152:155], v[16:19]
	v_mfma_f32_16x16x32_bf16 v[12:15], v[224:227], v[168:171], v[12:15]
	v_mfma_f32_16x16x32_bf16 v[8:11], v[232:235], v[168:171], v[8:11]
	v_mfma_f32_16x16x32_bf16 v[4:7], v[224:227], v[176:179], v[4:7]
	v_mfma_f32_16x16x32_bf16 v[0:3], v[232:235], v[176:179], v[0:3]
	v_mfma_f32_16x16x32_bf16 v[28:31], v[228:231], v[148:151], v[28:31]
	v_mfma_f32_16x16x32_bf16 v[24:27], v[236:239], v[148:151], v[24:27]
	v_mfma_f32_16x16x32_bf16 v[20:23], v[228:231], v[156:159], v[20:23]
	v_mfma_f32_16x16x32_bf16 v[16:19], v[236:239], v[156:159], v[16:19]
	v_mfma_f32_16x16x32_bf16 v[12:15], v[228:231], v[172:175], v[12:15]
	v_mfma_f32_16x16x32_bf16 v[8:11], v[236:239], v[172:175], v[8:11]
	v_mfma_f32_16x16x32_bf16 v[4:7], v[228:231], v[180:183], v[4:7]
	v_mfma_f32_16x16x32_bf16 v[0:3], v[236:239], v[180:183], v[0:3]
	s_barrier
	ds_read_b128 v[128:131], v222
	ds_read_b128 v[132:135], v222 offset:1024
	ds_read_b128 v[136:139], v222 offset:2048
	ds_read_b128 v[140:143], v222 offset:3072
	v_readfirstlane_b32 s22, v206
	s_add_i32 s19, s12, 0x40100
	s_mov_b32 m0, s22
	v_readfirstlane_b32 s22, v207
	ds_read_b128 v[144:147], v217 offset:32768
	ds_read_b128 v[148:151], v217 offset:33792
	ds_read_b128 v[152:155], v218 offset:32768
	ds_read_b128 v[156:159], v218 offset:33792
	ds_read_b128 v[168:171], v219 offset:32768
	ds_read_b128 v[172:175], v219 offset:33792
	ds_read_b128 v[176:179], v220 offset:32768
	ds_read_b128 v[180:183], v220 offset:33792
	buffer_load_dwordx4 v198, s[68:71], s19 offen lds
	s_mov_b32 m0, s22
	s_nop 0
	buffer_load_dwordx4 v199, s[68:71], s19 offen lds
	s_waitcnt lgkmcnt(8)
	s_barrier
	s_waitcnt lgkmcnt(0)
	s_waitcnt lgkmcnt(7)
	v_mfma_f32_16x16x32_bf16 v[124:127], v[128:131], v[144:147], v[124:127]
	v_mfma_f32_16x16x32_bf16 v[120:123], v[136:139], v[144:147], v[120:123]
	s_waitcnt lgkmcnt(5)
	v_mfma_f32_16x16x32_bf16 v[116:119], v[128:131], v[152:155], v[116:119]
	v_mfma_f32_16x16x32_bf16 v[112:115], v[136:139], v[152:155], v[112:115]
	s_waitcnt lgkmcnt(3)
	v_mfma_f32_16x16x32_bf16 v[108:111], v[128:131], v[168:171], v[108:111]
	v_mfma_f32_16x16x32_bf16 v[104:107], v[136:139], v[168:171], v[104:107]
	s_waitcnt lgkmcnt(1)
	v_mfma_f32_16x16x32_bf16 v[100:103], v[128:131], v[176:179], v[100:103]
	v_mfma_f32_16x16x32_bf16 v[96:99], v[136:139], v[176:179], v[96:99]
	v_mfma_f32_16x16x32_bf16 v[124:127], v[132:135], v[148:151], v[124:127]
	v_mfma_f32_16x16x32_bf16 v[120:123], v[140:143], v[148:151], v[120:123]
	v_mfma_f32_16x16x32_bf16 v[116:119], v[132:135], v[156:159], v[116:119]
	v_mfma_f32_16x16x32_bf16 v[112:115], v[140:143], v[156:159], v[112:115]
	v_mfma_f32_16x16x32_bf16 v[108:111], v[132:135], v[172:175], v[108:111]
	v_mfma_f32_16x16x32_bf16 v[104:107], v[140:143], v[172:175], v[104:107]
	s_waitcnt lgkmcnt(0)
	v_mfma_f32_16x16x32_bf16 v[100:103], v[132:135], v[180:183], v[100:103]
	v_mfma_f32_16x16x32_bf16 v[96:99], v[140:143], v[180:183], v[96:99]
	s_barrier
	v_readfirstlane_b32 s22, v208
	s_add_i32 s19, s13, 0x180
	s_mov_b32 m0, s22
	v_readfirstlane_b32 s22, v209
	ds_read_b128 v[224:227], v223
	ds_read_b128 v[228:231], v223 offset:1024
	ds_read_b128 v[232:235], v223 offset:2048
	ds_read_b128 v[236:239], v223 offset:3072
	buffer_load_dwordx4 v198, s[72:75], s19 offen lds
	s_mov_b32 m0, s22
	s_nop 0
	buffer_load_dwordx4 v199, s[72:75], s19 offen lds
	s_barrier
	s_waitcnt lgkmcnt(0)
	s_waitcnt lgkmcnt(3)
	v_mfma_f32_16x16x32_bf16 v[92:95], v[224:227], v[144:147], v[92:95]
	s_waitcnt lgkmcnt(1)
	v_mfma_f32_16x16x32_bf16 v[88:91], v[232:235], v[144:147], v[88:91]
	v_mfma_f32_16x16x32_bf16 v[84:87], v[224:227], v[152:155], v[84:87]
	v_mfma_f32_16x16x32_bf16 v[80:83], v[232:235], v[152:155], v[80:83]
	v_mfma_f32_16x16x32_bf16 v[76:79], v[224:227], v[168:171], v[76:79]
	v_mfma_f32_16x16x32_bf16 v[72:75], v[232:235], v[168:171], v[72:75]
	v_mfma_f32_16x16x32_bf16 v[68:71], v[224:227], v[176:179], v[68:71]
	v_mfma_f32_16x16x32_bf16 v[64:67], v[232:235], v[176:179], v[64:67]
	v_mfma_f32_16x16x32_bf16 v[92:95], v[228:231], v[148:151], v[92:95]
	s_waitcnt lgkmcnt(0)
	v_mfma_f32_16x16x32_bf16 v[88:91], v[236:239], v[148:151], v[88:91]
	v_mfma_f32_16x16x32_bf16 v[84:87], v[228:231], v[156:159], v[84:87]
	v_mfma_f32_16x16x32_bf16 v[80:83], v[236:239], v[156:159], v[80:83]
	v_mfma_f32_16x16x32_bf16 v[76:79], v[228:231], v[172:175], v[76:79]
	v_mfma_f32_16x16x32_bf16 v[72:75], v[236:239], v[172:175], v[72:75]
	v_mfma_f32_16x16x32_bf16 v[68:71], v[228:231], v[180:183], v[68:71]
	v_mfma_f32_16x16x32_bf16 v[64:67], v[236:239], v[180:183], v[64:67]
	v_readfirstlane_b32 s19, v210
	s_addk_i32 s12, 0x180
	s_mov_b32 m0, s19
	v_readfirstlane_b32 s19, v211
	s_barrier
	ds_read_b128 v[144:147], v217 offset:49152
	ds_read_b128 v[148:151], v217 offset:50176
	ds_read_b128 v[152:155], v218 offset:49152
	ds_read_b128 v[156:159], v218 offset:50176
	ds_read_b128 v[168:171], v219 offset:49152
	ds_read_b128 v[172:175], v219 offset:50176
	ds_read_b128 v[176:179], v220 offset:49152
	ds_read_b128 v[180:183], v220 offset:50176
	buffer_load_dwordx4 v198, s[68:71], s12 offen lds
	s_mov_b32 m0, s19
	s_nop 0
	buffer_load_dwordx4 v199, s[68:71], s12 offen lds
	s_barrier
; #define G_STAGE(P, RS, br, kt) do { const int _so = ((br) * G_K + (kt) * G_BK) * 2; \
;     __builtin_amdgcn_raw_ptr_buffer_load_lds(RS, (__attribute__((address_space(3))) unsigned*)((char*)(P) + tid * 16), 16, (int)voff0, _so, 0, 0); \
;     __builtin_amdgcn_raw_ptr_buffer_load_lds(RS, (__attribute__((address_space(3))) unsigned*)((char*)(P) + tid * 16 + 8192), 16, (int)voff1, _so, 0, 0); } while (0)
; #define G_LDA(dst, b, h) for (int m = 0; m < 4; ++m) for (int k = 0; k < 2; ++k) \
;     dst[m][k] = *reinterpret_cast<const bf16x8*>((char*)G_SA(b, h) + lds_byte(wr * 64 + m * 16 + fr, k * 32 + fq * 8))
; #define G_LDB(dst, b, h) for (int n = 0; n < 2; ++n) for (int k = 0; k < 2; ++k) \
;     dst[n][k] = *reinterpret_cast<const bf16x8*>((char*)G_SB(b, h) + lds_byte(wc * 32 + n * 16 + fr, k * 32 + fq * 8))
; #define G_MMA(ai, bj, At, Bt_) do { __builtin_amdgcn_s_setprio(1); \
;     for (int m = 0; m < 4; ++m) for (int n = 0; n < 2; ++n) for (int k = 0; k < 2; ++k) \
;       acc[ai][bj][m][n] = __builtin_amdgcn_mfma_f32_16x16x32_bf16(Bt_[n][k], At[m][k], acc[ai][bj][m][n], 0, 0, 0); \
;     __builtin_amdgcn_s_setprio(0); } while (0)
; #define WAIT_V(n) asm volatile("s_waitcnt vmcnt(" #n ")" ::: "memory")
; #define WAIT_L(n) asm volatile("s_waitcnt lgkmcnt(" #n ")" ::: "memory")
; #define G_BAR __builtin_amdgcn_s_barrier()
; #define G_SCHED __builtin_amdgcn_sched_barrier(0)
; DEV void phase_gemm(const Params& p, int l, int mode) {
;     ...
;       G_LDA(At, 1, 1); G_STAGE(G_SA(1, 0), A, brow, t + 3);
;       G_BAR; WAIT_L(0); G_MMA(1, 0, At, B0); G_BAR; G_SCHED;
;       G_STAGE(G_SB(1, 1), Bt, bcol + G_HALF, t + 3);
;       WAIT_V(6); G_BAR; G_MMA(1, 1, At, B1); G_BAR;
;     }
;     { G_LDB(B0, 0, 0); G_LDA(At, 0, 0); G_STAGE(G_SA(1, 1), A, brow + G_HALF, nt - 1);
;       G_BAR; WAIT_L(0); G_MMA(0, 0, At, B0); G_BAR;
;       G_LDB(B1, 0, 1); G_BAR; WAIT_L(0); G_MMA(0, 1, At, B1); G_BAR;
;       G_LDA(At, 0, 1); WAIT_V(4); G_BAR; WAIT_L(0); G_MMA(1, 0, At, B0); G_MMA(1, 1, At, B1); G_BAR; }
	s_waitcnt lgkmcnt(0)
	s_waitcnt lgkmcnt(7)
	v_mfma_f32_16x16x32_bf16 v[60:63], v[128:131], v[144:147], v[60:63]
	v_mfma_f32_16x16x32_bf16 v[56:59], v[136:139], v[144:147], v[56:59]
	s_waitcnt lgkmcnt(5)
	v_mfma_f32_16x16x32_bf16 v[52:55], v[128:131], v[152:155], v[52:55]
	v_mfma_f32_16x16x32_bf16 v[48:51], v[136:139], v[152:155], v[48:51]
	s_waitcnt lgkmcnt(3)
	v_mfma_f32_16x16x32_bf16 v[44:47], v[128:131], v[168:171], v[44:47]
	v_mfma_f32_16x16x32_bf16 v[40:43], v[136:139], v[168:171], v[40:43]
	s_waitcnt lgkmcnt(1)
	v_mfma_f32_16x16x32_bf16 v[36:39], v[128:131], v[176:179], v[36:39]
	v_mfma_f32_16x16x32_bf16 v[32:35], v[136:139], v[176:179], v[32:35]
	v_mfma_f32_16x16x32_bf16 v[60:63], v[132:135], v[148:151], v[60:63]
	v_mfma_f32_16x16x32_bf16 v[56:59], v[140:143], v[148:151], v[56:59]
	v_mfma_f32_16x16x32_bf16 v[52:55], v[132:135], v[156:159], v[52:55]
	v_mfma_f32_16x16x32_bf16 v[48:51], v[140:143], v[156:159], v[48:51]
	v_mfma_f32_16x16x32_bf16 v[44:47], v[132:135], v[172:175], v[44:47]
	v_mfma_f32_16x16x32_bf16 v[40:43], v[140:143], v[172:175], v[40:43]
	s_waitcnt lgkmcnt(0)
	v_mfma_f32_16x16x32_bf16 v[36:39], v[132:135], v[180:183], v[36:39]
	v_mfma_f32_16x16x32_bf16 v[32:35], v[140:143], v[180:183], v[32:35]
	s_barrier
	v_readfirstlane_b32 s12, v212
	s_add_i32 s13, s13, 0x40180
	s_mov_b32 m0, s12
	v_readfirstlane_b32 s12, v213
	buffer_load_dwordx4 v198, s[72:75], s13 offen lds
	s_mov_b32 m0, s12
	s_nop 0
	buffer_load_dwordx4 v199, s[72:75], s13 offen lds
	s_waitcnt vmcnt(6)
	s_barrier
	v_mfma_f32_16x16x32_bf16 v[28:31], v[224:227], v[144:147], v[28:31]
	v_mfma_f32_16x16x32_bf16 v[24:27], v[232:235], v[144:147], v[24:27]
	v_mfma_f32_16x16x32_bf16 v[20:23], v[224:227], v[152:155], v[20:23]
	v_mfma_f32_16x16x32_bf16 v[16:19], v[232:235], v[152:155], v[16:19]
	v_mfma_f32_16x16x32_bf16 v[12:15], v[224:227], v[168:171], v[12:15]
	v_mfma_f32_16x16x32_bf16 v[8:11], v[232:235], v[168:171], v[8:11]
	v_mfma_f32_16x16x32_bf16 v[4:7], v[224:227], v[176:179], v[4:7]
	v_mfma_f32_16x16x32_bf16 v[0:3], v[232:235], v[176:179], v[0:3]
	v_mfma_f32_16x16x32_bf16 v[28:31], v[228:231], v[148:151], v[28:31]
	v_mfma_f32_16x16x32_bf16 v[24:27], v[236:239], v[148:151], v[24:27]
	v_mfma_f32_16x16x32_bf16 v[20:23], v[228:231], v[156:159], v[20:23]
	v_mfma_f32_16x16x32_bf16 v[16:19], v[236:239], v[156:159], v[16:19]
	v_mfma_f32_16x16x32_bf16 v[12:15], v[228:231], v[172:175], v[12:15]
	v_mfma_f32_16x16x32_bf16 v[8:11], v[236:239], v[172:175], v[8:11]
	v_mfma_f32_16x16x32_bf16 v[4:7], v[228:231], v[180:183], v[4:7]
	v_mfma_f32_16x16x32_bf16 v[0:3], v[236:239], v[180:183], v[0:3]
	s_add_i32 s10, s10, 2
	s_addk_i32 s11, 0x100
	s_cmp_lt_u32 s10, 12
	s_barrier
	s_cbranch_scc1 .LBB0_211
	v_readfirstlane_b32 s9, v214
	s_add_i32 s8, s8, 0x40780
	s_mov_b32 m0, s9
	v_readfirstlane_b32 s9, v215
	ds_read_b128 v[128:131], v216
	ds_read_b128 v[132:135], v216 offset:1024
	ds_read_b128 v[136:139], v216 offset:2048
	ds_read_b128 v[140:143], v216 offset:3072
	ds_read_b128 v[144:147], v217
	ds_read_b128 v[148:151], v217 offset:1024
	ds_read_b128 v[152:155], v218
	ds_read_b128 v[156:159], v218 offset:1024
	ds_read_b128 v[168:171], v219
	ds_read_b128 v[172:175], v219 offset:1024
	ds_read_b128 v[176:179], v220
	ds_read_b128 v[180:183], v220 offset:1024
	buffer_load_dwordx4 v198, s[68:71], s8 offen lds
	s_mov_b32 m0, s9
	s_nop 0
	buffer_load_dwordx4 v199, s[68:71], s8 offen lds
	s_barrier
	s_waitcnt lgkmcnt(0)
	s_waitcnt lgkmcnt(7)
	v_mfma_f32_16x16x32_bf16 v[124:127], v[128:131], v[144:147], v[124:127]
	s_waitcnt lgkmcnt(5)
	v_mfma_f32_16x16x32_bf16 v[116:119], v[128:131], v[152:155], v[116:119]
	s_waitcnt lgkmcnt(3)
	v_mfma_f32_16x16x32_bf16 v[108:111], v[128:131], v[168:171], v[108:111]
	v_mfma_f32_16x16x32_bf16 v[104:107], v[136:139], v[168:171], v[104:107]
	s_waitcnt lgkmcnt(1)
	v_mfma_f32_16x16x32_bf16 v[100:103], v[128:131], v[176:179], v[100:103]
	v_mfma_f32_16x16x32_bf16 v[96:99], v[136:139], v[176:179], v[96:99]
	v_mfma_f32_16x16x32_bf16 v[124:127], v[132:135], v[148:151], v[124:127]
	v_mfma_f32_16x16x32_bf16 v[120:123], v[136:139], v[144:147], v[120:123]
	v_mfma_f32_16x16x32_bf16 v[116:119], v[132:135], v[156:159], v[116:119]
	v_mfma_f32_16x16x32_bf16 v[112:115], v[136:139], v[152:155], v[112:115]
	v_mfma_f32_16x16x32_bf16 v[108:111], v[132:135], v[172:175], v[108:111]
	v_mfma_f32_16x16x32_bf16 v[104:107], v[140:143], v[172:175], v[104:107]
	s_waitcnt lgkmcnt(0)
	v_mfma_f32_16x16x32_bf16 v[100:103], v[132:135], v[180:183], v[100:103]
	v_mfma_f32_16x16x32_bf16 v[96:99], v[140:143], v[180:183], v[96:99]
	v_mfma_f32_16x16x32_bf16 v[224:227], v[140:143], v[148:151], v[120:123]
	v_mfma_f32_16x16x32_bf16 v[228:231], v[140:143], v[156:159], v[112:115]
	s_barrier
	s_nop 0
	ds_read_b128 v[112:115], v221
	ds_read_b128 v[120:123], v221 offset:1024
	ds_read_b128 v[232:235], v221 offset:2048
	ds_read_b128 v[236:239], v221 offset:3072
	s_barrier
	s_waitcnt lgkmcnt(0)
	s_waitcnt lgkmcnt(3)
	v_mfma_f32_16x16x32_bf16 v[92:95], v[112:115], v[144:147], v[92:95]
	v_mfma_f32_16x16x32_bf16 v[84:87], v[112:115], v[152:155], v[84:87]
	v_mfma_f32_16x16x32_bf16 v[76:79], v[112:115], v[168:171], v[76:79]
	v_mfma_f32_16x16x32_bf16 v[68:71], v[112:115], v[176:179], v[68:71]
	s_waitcnt lgkmcnt(2)
	v_mfma_f32_16x16x32_bf16 v[92:95], v[120:123], v[148:151], v[92:95]
	s_waitcnt lgkmcnt(1)
	v_mfma_f32_16x16x32_bf16 v[88:91], v[232:235], v[144:147], v[88:91]
	v_mfma_f32_16x16x32_bf16 v[84:87], v[120:123], v[156:159], v[84:87]
	v_mfma_f32_16x16x32_bf16 v[80:83], v[232:235], v[152:155], v[80:83]
	v_mfma_f32_16x16x32_bf16 v[76:79], v[120:123], v[172:175], v[76:79]
	v_mfma_f32_16x16x32_bf16 v[72:75], v[232:235], v[168:171], v[72:75]
	v_mfma_f32_16x16x32_bf16 v[68:71], v[120:123], v[180:183], v[68:71]
	v_mfma_f32_16x16x32_bf16 v[64:67], v[232:235], v[176:179], v[64:67]
	s_waitcnt lgkmcnt(0)
	v_mfma_f32_16x16x32_bf16 v[144:147], v[236:239], v[148:151], v[88:91]
	v_mfma_f32_16x16x32_bf16 v[148:151], v[236:239], v[156:159], v[80:83]
	v_mfma_f32_16x16x32_bf16 v[152:155], v[236:239], v[172:175], v[72:75]
	v_mfma_f32_16x16x32_bf16 v[156:159], v[236:239], v[180:183], v[64:67]
	s_barrier
; #define G_LDA(dst, b, h) for (int m = 0; m < 4; ++m) for (int k = 0; k < 2; ++k) \
;     dst[m][k] = *reinterpret_cast<const bf16x8*>((char*)G_SA(b, h) + lds_byte(wr * 64 + m * 16 + fr, k * 32 + fq * 8))
; #define G_LDB(dst, b, h) for (int n = 0; n < 2; ++n) for (int k = 0; k < 2; ++k) \
;     dst[n][k] = *reinterpret_cast<const bf16x8*>((char*)G_SB(b, h) + lds_byte(wc * 32 + n * 16 + fr, k * 32 + fq * 8))
; #define G_MMA(ai, bj, At, Bt_) do { __builtin_amdgcn_s_setprio(1); \
;     for (int m = 0; m < 4; ++m) for (int n = 0; n < 2; ++n) for (int k = 0; k < 2; ++k) \
;       acc[ai][bj][m][n] = __builtin_amdgcn_mfma_f32_16x16x32_bf16(Bt_[n][k], At[m][k], acc[ai][bj][m][n], 0, 0, 0); \
;     __builtin_amdgcn_s_setprio(0); } while (0)
; #define WAIT_V(n) asm volatile("s_waitcnt vmcnt(" #n ")" ::: "memory")
; #define WAIT_L(n) asm volatile("s_waitcnt lgkmcnt(" #n ")" ::: "memory")
; #define G_BAR __builtin_amdgcn_s_barrier()
; DEV void phase_gemm(const Params& p, int l, int mode) {
;     ...
;       G_LDA(At, 0, 1); WAIT_V(4); G_BAR; WAIT_L(0); G_MMA(1, 0, At, B0); G_MMA(1, 1, At, B1); G_BAR; }
;     { G_LDB(B0, 1, 0); G_LDA(At, 1, 0); WAIT_V(2); G_BAR; WAIT_L(0); G_MMA(0, 0, At, B0); G_BAR;
;       G_LDB(B1, 1, 1); WAIT_V(0); G_BAR; WAIT_L(0); G_MMA(0, 1, At, B1); G_BAR;
	s_nop 0
	ds_read_b128 v[64:67], v217 offset:16384
	ds_read_b128 v[72:75], v217 offset:17408
	ds_read_b128 v[80:83], v218 offset:16384
	ds_read_b128 v[88:91], v218 offset:17408
	ds_read_b128 v[168:171], v219 offset:16384
	ds_read_b128 v[172:175], v219 offset:17408
	ds_read_b128 v[176:179], v220 offset:16384
	ds_read_b128 v[180:183], v220 offset:17408
	s_waitcnt vmcnt(4)
	s_barrier
	s_waitcnt lgkmcnt(0)
	s_waitcnt lgkmcnt(7)
	v_mfma_f32_16x16x32_bf16 v[60:63], v[128:131], v[64:67], v[60:63]
	v_mfma_f32_16x16x32_bf16 v[56:59], v[136:139], v[64:67], v[56:59]
	s_waitcnt lgkmcnt(5)
	v_mfma_f32_16x16x32_bf16 v[52:55], v[128:131], v[80:83], v[52:55]
	s_waitcnt lgkmcnt(3)
	v_mfma_f32_16x16x32_bf16 v[44:47], v[128:131], v[168:171], v[44:47]
	s_waitcnt lgkmcnt(1)
	v_mfma_f32_16x16x32_bf16 v[36:39], v[128:131], v[176:179], v[36:39]
	v_mfma_f32_16x16x32_bf16 v[60:63], v[132:135], v[72:75], v[60:63]
	v_mfma_f32_16x16x32_bf16 v[240:243], v[140:143], v[72:75], v[56:59]
	v_mfma_f32_16x16x32_bf16 v[52:55], v[132:135], v[88:91], v[52:55]
	v_mfma_f32_16x16x32_bf16 v[48:51], v[136:139], v[80:83], v[48:51]
	v_mfma_f32_16x16x32_bf16 v[44:47], v[132:135], v[172:175], v[44:47]
	v_mfma_f32_16x16x32_bf16 v[40:43], v[136:139], v[168:171], v[40:43]
	s_waitcnt lgkmcnt(0)
	v_mfma_f32_16x16x32_bf16 v[36:39], v[132:135], v[180:183], v[36:39]
	v_mfma_f32_16x16x32_bf16 v[32:35], v[136:139], v[176:179], v[32:35]
	v_mfma_f32_16x16x32_bf16 v[244:247], v[140:143], v[88:91], v[48:51]
	v_mfma_f32_16x16x32_bf16 v[248:251], v[140:143], v[172:175], v[40:43]
	v_mfma_f32_16x16x32_bf16 v[128:131], v[140:143], v[180:183], v[32:35]
	v_mfma_f32_16x16x32_bf16 v[12:15], v[112:115], v[168:171], v[12:15]
	v_mfma_f32_16x16x32_bf16 v[4:7], v[112:115], v[176:179], v[4:7]
	v_mfma_f32_16x16x32_bf16 v[28:31], v[112:115], v[64:67], v[28:31]
	v_mfma_f32_16x16x32_bf16 v[24:27], v[232:235], v[64:67], v[24:27]
	v_mfma_f32_16x16x32_bf16 v[20:23], v[112:115], v[80:83], v[20:23]
	v_mfma_f32_16x16x32_bf16 v[16:19], v[232:235], v[80:83], v[16:19]
	v_mfma_f32_16x16x32_bf16 v[12:15], v[120:123], v[172:175], v[12:15]
	v_mfma_f32_16x16x32_bf16 v[8:11], v[232:235], v[168:171], v[8:11]
	v_mfma_f32_16x16x32_bf16 v[4:7], v[120:123], v[180:183], v[4:7]
	v_mfma_f32_16x16x32_bf16 v[0:3], v[232:235], v[176:179], v[0:3]
	v_mfma_f32_16x16x32_bf16 v[132:135], v[120:123], v[72:75], v[28:31]
	v_mfma_f32_16x16x32_bf16 v[136:139], v[236:239], v[72:75], v[24:27]
	v_mfma_f32_16x16x32_bf16 v[140:143], v[120:123], v[88:91], v[20:23]
	v_mfma_f32_16x16x32_bf16 v[184:187], v[236:239], v[88:91], v[16:19]
	v_mfma_f32_16x16x32_bf16 v[168:171], v[236:239], v[172:175], v[8:11]
	v_mfma_f32_16x16x32_bf16 v[172:175], v[236:239], v[180:183], v[0:3]
	s_barrier
	ds_read_b128 v[20:23], v222
	ds_read_b128 v[28:31], v222 offset:1024
	ds_read_b128 v[176:179], v222 offset:2048
	ds_read_b128 v[180:183], v222 offset:3072
	ds_read_b128 v[0:3], v217 offset:32768
	ds_read_b128 v[8:11], v217 offset:33792
	ds_read_b128 v[32:35], v218 offset:32768
	ds_read_b128 v[40:43], v218 offset:33792
	ds_read_b128 v[232:235], v219 offset:32768
	ds_read_b128 v[236:239], v219 offset:33792
	ds_read_b128 v[192:195], v220 offset:32768
	ds_read_b128 v[164:167], v220 offset:33792
	s_waitcnt vmcnt(2)
	s_barrier
	s_waitcnt lgkmcnt(0)
	s_waitcnt lgkmcnt(7)
	v_mfma_f32_16x16x32_bf16 v[16:19], v[20:23], v[0:3], v[124:127]
	s_waitcnt lgkmcnt(6)
	v_mfma_f32_16x16x32_bf16 v[120:123], v[28:31], v[8:11], v[16:19]
	v_mfma_f32_16x16x32_bf16 v[16:19], v[176:179], v[0:3], v[224:227]
	v_mfma_f32_16x16x32_bf16 v[112:115], v[180:183], v[8:11], v[16:19]
	s_waitcnt lgkmcnt(5)
	v_mfma_f32_16x16x32_bf16 v[16:19], v[20:23], v[32:35], v[116:119]
	s_waitcnt lgkmcnt(4)
	v_mfma_f32_16x16x32_bf16 v[88:91], v[28:31], v[40:43], v[16:19]
	v_mfma_f32_16x16x32_bf16 v[16:19], v[176:179], v[32:35], v[228:231]
	v_mfma_f32_16x16x32_bf16 v[80:83], v[180:183], v[40:43], v[16:19]
	s_waitcnt lgkmcnt(3)
	v_mfma_f32_16x16x32_bf16 v[16:19], v[20:23], v[232:235], v[108:111]
	s_waitcnt lgkmcnt(2)
	v_mfma_f32_16x16x32_bf16 v[108:111], v[28:31], v[236:239], v[16:19]
	v_mfma_f32_16x16x32_bf16 v[16:19], v[176:179], v[232:235], v[104:107]
	v_mfma_f32_16x16x32_bf16 v[56:59], v[180:183], v[236:239], v[16:19]
	s_waitcnt lgkmcnt(1)
	v_mfma_f32_16x16x32_bf16 v[16:19], v[20:23], v[192:195], v[100:103]
	s_waitcnt lgkmcnt(0)
	v_mfma_f32_16x16x32_bf16 v[48:51], v[28:31], v[164:167], v[16:19]
	v_mfma_f32_16x16x32_bf16 v[16:19], v[176:179], v[192:195], v[96:99]
	v_mfma_f32_16x16x32_bf16 v[24:27], v[180:183], v[164:167], v[16:19]
	s_barrier
; #define G_LDA(dst, b, h) for (int m = 0; m < 4; ++m) for (int k = 0; k < 2; ++k) \
;     dst[m][k] = *reinterpret_cast<const bf16x8*>((char*)G_SA(b, h) + lds_byte(wr * 64 + m * 16 + fr, k * 32 + fq * 8))
; #define G_LDB(dst, b, h) for (int n = 0; n < 2; ++n) for (int k = 0; k < 2; ++k) \
;     dst[n][k] = *reinterpret_cast<const bf16x8*>((char*)G_SB(b, h) + lds_byte(wc * 32 + n * 16 + fr, k * 32 + fq * 8))
; #define G_MMA(ai, bj, At, Bt_) do { __builtin_amdgcn_s_setprio(1); \
;     for (int m = 0; m < 4; ++m) for (int n = 0; n < 2; ++n) for (int k = 0; k < 2; ++k) \
;       acc[ai][bj][m][n] = __builtin_amdgcn_mfma_f32_16x16x32_bf16(Bt_[n][k], At[m][k], acc[ai][bj][m][n], 0, 0, 0); \
;     __builtin_amdgcn_s_setprio(0); } while (0)
; #define WAIT_V(n) asm volatile("s_waitcnt vmcnt(" #n ")" ::: "memory")
; #define WAIT_L(n) asm volatile("s_waitcnt lgkmcnt(" #n ")" ::: "memory")
; #define G_BAR __builtin_amdgcn_s_barrier()
; DEV void phase_gemm(const Params& p, int l, int mode) {
;     ...
;     { G_LDB(B0, 1, 0); G_LDA(At, 1, 0); WAIT_V(2); G_BAR; WAIT_L(0); G_MMA(0, 0, At, B0); G_BAR;
;       G_LDB(B1, 1, 1); WAIT_V(0); G_BAR; WAIT_L(0); G_MMA(0, 1, At, B1); G_BAR;
;       G_LDA(At, 1, 1); G_BAR; WAIT_L(0); G_MMA(1, 0, At, B0); G_MMA(1, 1, At, B1); G_BAR; }
;     if (wr == 0) G_BAR;
;     __syncthreads();
	ds_read_b128 v[224:227], v223
	ds_read_b128 v[228:231], v223 offset:1024
	ds_read_b128 v[188:191], v223 offset:2048
	s_nop 1
	ds_read_b128 v[16:19], v223 offset:3072
	s_waitcnt vmcnt(0)
	s_barrier
	s_waitcnt lgkmcnt(0)
	s_waitcnt lgkmcnt(3)
	v_mfma_f32_16x16x32_bf16 v[64:67], v[224:227], v[0:3], v[92:95]
	s_waitcnt lgkmcnt(1)
	v_mfma_f32_16x16x32_bf16 v[0:3], v[188:191], v[0:3], v[144:147]
	s_waitcnt lgkmcnt(0)
	v_mfma_f32_16x16x32_bf16 v[96:99], v[16:19], v[8:11], v[0:3]
	v_mfma_f32_16x16x32_bf16 v[0:3], v[224:227], v[32:35], v[84:87]
	v_mfma_f32_16x16x32_bf16 v[72:75], v[228:231], v[40:43], v[0:3]
	v_mfma_f32_16x16x32_bf16 v[0:3], v[188:191], v[32:35], v[148:151]
	v_mfma_f32_16x16x32_bf16 v[104:107], v[228:231], v[8:11], v[64:67]
	v_mfma_f32_16x16x32_bf16 v[64:67], v[16:19], v[40:43], v[0:3]
	v_mfma_f32_16x16x32_bf16 v[0:3], v[224:227], v[232:235], v[76:79]
	v_mfma_f32_16x16x32_bf16 v[40:43], v[228:231], v[236:239], v[0:3]
	v_mfma_f32_16x16x32_bf16 v[0:3], v[188:191], v[232:235], v[152:155]
	v_mfma_f32_16x16x32_bf16 v[32:35], v[16:19], v[236:239], v[0:3]
	v_mfma_f32_16x16x32_bf16 v[0:3], v[224:227], v[192:195], v[68:71]
	v_mfma_f32_16x16x32_bf16 v[8:11], v[228:231], v[164:167], v[0:3]
	v_mfma_f32_16x16x32_bf16 v[0:3], v[188:191], v[192:195], v[156:159]
	v_mfma_f32_16x16x32_bf16 v[0:3], v[16:19], v[164:167], v[0:3]
	s_barrier
	ds_read_b128 v[68:71], v217 offset:49152
	ds_read_b128 v[76:79], v217 offset:50176
	ds_read_b128 v[144:147], v218 offset:49152
	ds_read_b128 v[148:151], v218 offset:50176
	ds_read_b128 v[152:155], v219 offset:49152
	ds_read_b128 v[156:159], v219 offset:50176
	ds_read_b128 v[164:167], v220 offset:49152
	ds_read_b128 v[192:195], v220 offset:50176
	s_barrier
	s_waitcnt lgkmcnt(0)
	s_waitcnt lgkmcnt(7)
	v_mfma_f32_16x16x32_bf16 v[60:63], v[20:23], v[68:71], v[60:63]
	s_waitcnt lgkmcnt(6)
	v_mfma_f32_16x16x32_bf16 v[124:127], v[28:31], v[76:79], v[60:63]
	v_mfma_f32_16x16x32_bf16 v[60:63], v[176:179], v[68:71], v[240:243]
	s_waitcnt lgkmcnt(5)
	v_mfma_f32_16x16x32_bf16 v[52:55], v[20:23], v[144:147], v[52:55]
	s_waitcnt lgkmcnt(3)
	v_mfma_f32_16x16x32_bf16 v[44:47], v[20:23], v[152:155], v[44:47]
	s_waitcnt lgkmcnt(1)
	v_mfma_f32_16x16x32_bf16 v[20:23], v[20:23], v[164:167], v[36:39]
	v_mfma_f32_16x16x32_bf16 v[116:119], v[180:183], v[76:79], v[60:63]
	v_mfma_f32_16x16x32_bf16 v[92:95], v[28:31], v[148:151], v[52:55]
	v_mfma_f32_16x16x32_bf16 v[52:55], v[176:179], v[144:147], v[244:247]
	v_mfma_f32_16x16x32_bf16 v[60:63], v[28:31], v[156:159], v[44:47]
	v_mfma_f32_16x16x32_bf16 v[44:47], v[176:179], v[152:155], v[248:251]
	s_waitcnt lgkmcnt(0)
	v_mfma_f32_16x16x32_bf16 v[28:31], v[28:31], v[192:195], v[20:23]
	v_mfma_f32_16x16x32_bf16 v[20:23], v[176:179], v[164:167], v[128:131]
	v_mfma_f32_16x16x32_bf16 v[84:87], v[180:183], v[148:151], v[52:55]
	v_mfma_f32_16x16x32_bf16 v[52:55], v[180:183], v[156:159], v[44:47]
	v_mfma_f32_16x16x32_bf16 v[20:23], v[180:183], v[192:195], v[20:23]
	v_mfma_f32_16x16x32_bf16 v[36:39], v[224:227], v[68:71], v[132:135]
	v_mfma_f32_16x16x32_bf16 v[240:243], v[228:231], v[76:79], v[36:39]
	v_mfma_f32_16x16x32_bf16 v[36:39], v[188:191], v[68:71], v[136:139]
	v_mfma_f32_16x16x32_bf16 v[100:103], v[16:19], v[76:79], v[36:39]
	v_mfma_f32_16x16x32_bf16 v[36:39], v[224:227], v[144:147], v[140:143]
	v_mfma_f32_16x16x32_bf16 v[12:15], v[224:227], v[152:155], v[12:15]
	v_mfma_f32_16x16x32_bf16 v[76:79], v[228:231], v[148:151], v[36:39]
	v_mfma_f32_16x16x32_bf16 v[36:39], v[188:191], v[144:147], v[184:187]
	v_mfma_f32_16x16x32_bf16 v[44:47], v[228:231], v[156:159], v[12:15]
	v_mfma_f32_16x16x32_bf16 v[12:15], v[188:191], v[152:155], v[168:171]
	v_mfma_f32_16x16x32_bf16 v[4:7], v[224:227], v[164:167], v[4:7]
	v_mfma_f32_16x16x32_bf16 v[68:71], v[16:19], v[148:151], v[36:39]
	v_mfma_f32_16x16x32_bf16 v[36:39], v[16:19], v[156:159], v[12:15]
	v_mfma_f32_16x16x32_bf16 v[12:15], v[228:231], v[192:195], v[4:7]
	v_mfma_f32_16x16x32_bf16 v[4:7], v[188:191], v[164:167], v[172:175]
	v_mfma_f32_16x16x32_bf16 v[4:7], v[16:19], v[192:195], v[4:7]
	s_setprio 0
	s_barrier
	s_mov_b64 s[8:9], exec
	v_readlane_b32 s10, v255, 27
	v_readlane_b32 s11, v255, 28
	s_and_b64 s[10:11], s[8:9], s[10:11]
	s_mov_b64 exec, s[10:11]
	s_cbranch_execz .LBB0_214
	s_barrier
